# P1 prologue: gate-weight staging with 4 loads in flight (was 4 serial load/wait/ds_write), gatef rows computed by the row-less blocks 248..255 instead of blocks 0..47; on top of P5 epilogue pipelining
# baseline (speedup 1.0000x reference)
; __device__ __forceinline__ void phase1(const Args& a, LAS unsigned char* L) {
;     ...
;     for (int r = bid; r < 48; r += G)
;         for (int c = tid; c < DM; c += 512) { float s = bada[2048 + c];
; #pragma unroll
;             for (int q = 0; q < 4; ++q) s += modp[(size_t)(q * 48 + r) * 3072 + 2048 + c];
;             gatef[r * DM + c] = s; }
.LBB0_101:
	s_or_b64 exec, exec, s[0:1]
	s_add_u32 s22, s28, 0x1e400000
	s_waitcnt lgkmcnt(0)
	v_mov_b32_e32 v0, v180
	s_addc_u32 s23, s29, 0
	s_barrier
	s_cmp_lt_i32 s2, 0xf8
	v_readfirstlane_b32 s12, v0
	s_cbranch_scc1 .LBB0_107
	s_mov_b32 s98, s2
	s_mov_b32 s99, s30
	s_sub_i32 s2, s2, 0xf8
	s_mov_b32 s30, 8
	v_ashrrev_i32_e32 v1, 31, v0
	s_movk_i32 s0, 0x400
	v_lshlrev_b64 v[8:9], 2, v[0:1]
	v_cmp_gt_i32_e32 vcc, s0, v0
	v_lshl_add_u64 v[4:5], s[54:55], 0, v[8:9]
	s_mov_b64 s[0:1], 0x2000
	s_lshl_b32 s13, s30, 10
	v_lshl_add_u64 v[4:5], v[4:5], 0, s[0:1]
	s_mul_i32 s0, s2, 0x3000
	s_mul_hi_i32 s1, s2, 0x3000
	s_add_u32 s0, s28, s0
	s_addc_u32 s1, s29, s1
	v_lshl_add_u64 v[6:7], s[0:1], 0, v[8:9]
	s_mov_b64 s[0:1], 0x1e102000
	v_lshl_add_u64 v[8:9], s[28:29], 0, v[8:9]
	v_add_u32_e32 v18, 0xfffffe00, v0
	v_lshl_add_u32 v2, s2, 10, v0
	v_lshl_add_u64 v[6:7], v[6:7], 0, s[0:1]
	s_mul_hi_i32 s5, s30, 0x3000
	s_mul_i32 s4, s30, 0x3000
	v_lshl_add_u64 v[8:9], v[8:9], 0, s[0:1]
	s_add_i32 s14, s2, 48
	s_add_i32 s15, s2, 0x60
	s_add_i32 s16, s2, 0x90
	s_movk_i32 s17, 0x1ff
	v_mov_b32_e32 v1, 0x3000
	s_mov_b32 s33, s2
	s_branch .LBB0_104

; #define LAS __attribute__((address_space(3)))
; __device__ __forceinline__ void phase1(const Args& a, LAS unsigned char* L) {
;     ...
;     LAS f32x4* wg = (LAS f32x4*)L;
;     for (int e = tid; e < 2048; e += 512) { const int ln = e & 63, q = e >> 6, half = q & 1, ji = q >> 1, k = 4 * ln + 256 * (ji >> 2) + (ji & 3);
;         wg[e] = *(const f32x4*)(a.in[11] + (size_t)k * WIN_LD + 7168 + half * 4); }
;     __syncthreads();
.Lp1_gf_done:
	s_mov_b32 s2, s98
	s_mov_b32 s30, s99
.LBB0_107:
	s_movk_i32 s0, 0x800
	v_cmp_gt_i32_e32 vcc, s0, v0
	s_and_saveexec_b64 s[0:1], vcc
	s_cbranch_execz .LBB0_110
	v_lshl_add_u32 v1, v0, 4, 0
	s_movk_i32 s6, 0x7020
	s_add_u32 s4, s58, 0x7000
	s_addc_u32 s5, s59, 0
	v_mov_b64_e32 v[2:3], s[4:5]
	v_mov_b32_e32 v5, 0
	v_add_u32_e32 v7, 0, v0
	v_lshlrev_b32_e32 v6, 2, v7
	v_ashrrev_i32_e32 v4, 1, v7
	v_and_b32_e32 v8, 0xfc, v6
	v_bfe_u32 v9, v7, 7, 2
	v_and_b32_e32 v11, 0xffffff00, v4
	v_lshrrev_b32_e32 v10, 2, v7
	v_or3_b32 v8, v8, v11, v9
	v_and_b32_e32 v4, 16, v10
	v_mad_i64_i32 v[8:9], s[8:9], v8, s6, v[2:3]
	v_lshl_add_u64 v[8:9], v[8:9], 0, v[4:5]
	global_load_dwordx4 v[12:15], v[8:9], off
	v_add_u32_e32 v7, 512, v0
	v_lshlrev_b32_e32 v6, 2, v7
	v_ashrrev_i32_e32 v4, 1, v7
	v_and_b32_e32 v8, 0xfc, v6
	v_bfe_u32 v9, v7, 7, 2
	v_and_b32_e32 v11, 0xffffff00, v4
	v_lshrrev_b32_e32 v10, 2, v7
	v_or3_b32 v8, v8, v11, v9
	v_and_b32_e32 v4, 16, v10
	v_mad_i64_i32 v[8:9], s[8:9], v8, s6, v[2:3]
	v_lshl_add_u64 v[8:9], v[8:9], 0, v[4:5]
	global_load_dwordx4 v[16:19], v[8:9], off
	v_add_u32_e32 v7, 1024, v0
	v_lshlrev_b32_e32 v6, 2, v7
	v_ashrrev_i32_e32 v4, 1, v7
	v_and_b32_e32 v8, 0xfc, v6
	v_bfe_u32 v9, v7, 7, 2
	v_and_b32_e32 v11, 0xffffff00, v4
	v_lshrrev_b32_e32 v10, 2, v7
	v_or3_b32 v8, v8, v11, v9
	v_and_b32_e32 v4, 16, v10
	v_mad_i64_i32 v[8:9], s[8:9], v8, s6, v[2:3]
	v_lshl_add_u64 v[8:9], v[8:9], 0, v[4:5]
	global_load_dwordx4 v[20:23], v[8:9], off
	v_add_u32_e32 v7, 1536, v0
	v_lshlrev_b32_e32 v6, 2, v7
	v_ashrrev_i32_e32 v4, 1, v7
	v_and_b32_e32 v8, 0xfc, v6
	v_bfe_u32 v9, v7, 7, 2
	v_and_b32_e32 v11, 0xffffff00, v4
	v_lshrrev_b32_e32 v10, 2, v7
	v_or3_b32 v8, v8, v11, v9
	v_and_b32_e32 v4, 16, v10
	v_mad_i64_i32 v[8:9], s[8:9], v8, s6, v[2:3]
	v_lshl_add_u64 v[8:9], v[8:9], 0, v[4:5]
	global_load_dwordx4 v[24:27], v[8:9], off
	s_waitcnt vmcnt(0)
	ds_write_b128 v1, v[12:15]
	ds_write_b128 v1, v[16:19] offset:8192
	ds_write_b128 v1, v[20:23] offset:16384
	ds_write_b128 v1, v[24:27] offset:24576
